# q/kv projection epilogues: LDS-DMA touch of the 7 later rows' partial-sum records alongside the first row's load
# speedup vs baseline: 1.0043x; 1.0037x over previous
; __device__ __forceinline__ u32x4 pack8(const f32x4& a, const f32x4& b) { u32x4 w; w.x = cvt_pk_bf16(a[0], a[1]); w.y = cvt_pk_bf16(a[2], a[3]); w.z = cvt_pk_bf16(b[0], b[1]); w.w = cvt_pk_bf16(b[2], b[3]); return w; }
; __device__ __forceinline__ float hsum4(const f32x4& v) { return (v[0] + v[1]) + (v[2] + v[3]); }
;     __device__ __forceinline__ void operator()(const f32x4 (&acc)[2][2][4][2], const Unit& u, int wr, int wc, int fr, int fq) const {
;         EPI_LAUNDER const int cb = wc * 32 + 8 * fq;
;         f32x4 rnx = *(const f32x4*)(rscq + 4 * (size_t)(u.pm * BM + wr * 64 + fr));
;         EPI_ROWS_BEGIN
;             const float r = rsqrtf(hsum4(rnx) * (1.f / 256.f) + EPS) * QSCALE;
;             { const int nx_ = ai * 4 + m + 1; if (nx_ < 8) rnx = *(const f32x4*)(rscq + 4 * (size_t)(u.pm * BM + (nx_ >> 2) * HALF + wr * 64 + (nx_ & 3) * 16 + fr)); }
;             if (u.pn < 2) {
; #pragma unroll
;                 for (int bj = 0; bj < 2; ++bj) *(u32x4*)(qn + (size_t)row * 512 + u.pn * 256 + bj * HALF + cb) = pack8(acc[ai][bj][m][0] * r, acc[ai][bj][m][1] * r);
;             } else { const int pos = row & (SEQ - 1); const f32x4 cs = *(const f32x4*)(cosT + pos * 16 + 4 * fq), sn = *(const f32x4*)(sinT + pos * 16 + 4 * fq);
; #pragma unroll
;                 for (int bj = 0; bj < 2; ++bj) { const f32x4 x1 = acc[ai][bj][m][0] * r, x2 = acc[ai][bj][m][1] * r;
;                     *(u32x4*)(qp + (size_t)row * 256 + bj * HALF + cb) = pack8(x1 * cs - x2 * sn, x1 * sn + x2 * cs); }
;             }
.LBB0_813:
	s_lshl_b32 s41, s6, 8
	v_mbcnt_lo_u32_b32 v0, -1, 0
	v_mbcnt_hi_u32_b32 v0, -1, v0
	s_add_i32 s1, s41, s73
	v_and_b32_e32 v134, 15, v0
	v_or_b32_e32 v130, s1, v134
	v_ashrrev_i32_e32 v131, 31, v130
	v_lshl_add_u64 v[130:131], v[130:131], 4, s[14:15]
	s_mov_b32 s98, m0
	s_mov_b32 m0, 0x20400
	s_nop 0
	global_load_lds_dword v[130:131], off offset:256
	global_load_lds_dword v[130:131], off offset:512
	global_load_lds_dword v[130:131], off offset:768
	global_load_lds_dword v[130:131], off offset:2048
	global_load_lds_dword v[130:131], off offset:2304
	global_load_lds_dword v[130:131], off offset:2560
	global_load_lds_dword v[130:131], off offset:2816
	s_mov_b32 m0, s98
	global_load_dwordx4 v[130:133], v[130:131], off
	v_ashrrev_i32_e32 v0, 4, v0
	v_lshl_add_u32 v146, v0, 3, s78
	v_or_b32_e32 v159, s73, v134
	v_lshlrev_b32_e32 v134, 2, v0
	v_mov_b32_e32 v252, 0x358637bd
	v_add_u32_e32 v148, s41, v159
	v_add_u32_e32 v152, 16, v148
	v_ashrrev_i32_e32 v153, 31, v152
	s_cmp_gt_i32 s10, 1
	v_ashrrev_i32_e32 v135, 31, v134
	s_cselect_b64 s[48:49], -1, 0
	v_ashrrev_i32_e32 v147, 31, v146
	s_mov_b64 s[6:7], -1
	v_lshlrev_b64 v[150:151], 2, v[134:135]
	v_ashrrev_i32_e32 v149, 31, v148
	s_waitcnt vmcnt(0)
	v_mov_b32_e32 v136, v131
	v_mov_b32_e32 v137, v132
	v_mov_b32_e32 v131, v133
	v_pk_add_f32 v[130:131], v[136:137], v[130:131]
	s_nop 0
	v_add_f32_e32 v0, v130, v131
	v_fmamk_f32 v0, v0, 0x3b800000, v252
	v_cmp_gt_f32_e32 vcc, s31, v0
	v_mul_f32_e32 v130, 0x4b800000, v0
	s_nop 0
	v_cndmask_b32_e32 v0, v0, v130, vcc
	v_rsq_f32_e32 v0, v0
	s_nop 0
	v_mul_f32_e32 v130, 0x45800000, v0
	v_cndmask_b32_e32 v0, v0, v130, vcc
	v_lshl_add_u64 v[130:131], v[152:153], 4, s[14:15]
	global_load_dwordx4 v[130:133], v[130:131], off
	v_mul_f32_e32 v154, 0x3e16c740, v0
	s_and_b64 vcc, exec, s[48:49]
	s_cbranch_vccz .LBB0_815
	v_lshlrev_b32_e32 v0, 6, v148
	v_and_b32_e32 v0, 0x1f3c0, v0
	v_lshl_add_u64 v[134:135], s[16:17], 0, v[0:1]
	v_lshl_add_u64 v[156:157], s[18:19], 0, v[0:1]
	v_lshl_add_u64 v[134:135], v[134:135], 0, v[150:151]
	v_lshl_add_u64 v[156:157], v[156:157], 0, v[150:151]
	global_load_dwordx4 v[134:137], v[134:135], off
	v_pk_mul_f32 v[168:169], v[124:125], v[154:155] op_sel_hi:[1,0]
	global_load_dwordx4 v[160:163], v[156:157], off
	v_pk_mul_f32 v[170:171], v[122:123], v[154:155] op_sel_hi:[1,0]
	v_pk_mul_f32 v[164:165], v[128:129], v[154:155] op_sel_hi:[1,0]
	v_pk_mul_f32 v[166:167], v[126:127], v[154:155] op_sel_hi:[1,0]
	v_lshlrev_b64 v[156:157], 9, v[148:149]
	v_lshl_add_u64 v[156:157], s[22:23], 0, v[156:157]
	s_mov_b64 s[6:7], 0
	s_waitcnt vmcnt(0)
	v_pk_mul_f32 v[172:173], v[168:169], v[162:163]
	v_pk_mul_f32 v[174:175], v[170:171], v[160:161]
	v_pk_fma_f32 v[172:173], v[164:165], v[136:137], v[172:173] neg_lo:[0,0,1] neg_hi:[0,0,1]
	v_pk_fma_f32 v[174:175], v[166:167], v[134:135], v[174:175] neg_lo:[0,0,1] neg_hi:[0,0,1]
	v_pk_mul_f32 v[164:165], v[164:165], v[162:163]
	v_pk_mul_f32 v[166:167], v[166:167], v[160:161]
	v_pk_fma_f32 v[168:169], v[168:169], v[136:137], v[164:165]
	v_pk_fma_f32 v[166:167], v[170:171], v[134:135], v[166:167]
	v_cvt_pk_bf16_f32 v164, v174, v175
	v_cvt_pk_bf16_f32 v165, v172, v173
	v_pk_mul_f32 v[170:171], v[114:115], v[154:155] op_sel_hi:[1,0]
	v_cvt_pk_bf16_f32 v166, v166, v167
	v_cvt_pk_bf16_f32 v167, v168, v169
	v_lshl_add_u64 v[168:169], v[146:147], 1, v[156:157]
	global_store_dwordx4 v[168:169], v[164:167], off
	v_pk_mul_f32 v[168:169], v[116:117], v[154:155] op_sel_hi:[1,0]
	v_pk_mul_f32 v[174:175], v[170:171], v[160:161]
	v_pk_mul_f32 v[164:165], v[120:121], v[154:155] op_sel_hi:[1,0]
	v_pk_mul_f32 v[166:167], v[118:119], v[154:155] op_sel_hi:[1,0]
	v_pk_mul_f32 v[172:173], v[168:169], v[162:163]
	v_pk_mul_f32 v[162:163], v[164:165], v[162:163]
	v_pk_mul_f32 v[160:161], v[166:167], v[160:161]
	v_pk_fma_f32 v[172:173], v[164:165], v[136:137], v[172:173] neg_lo:[0,0,1] neg_hi:[0,0,1]
	v_pk_fma_f32 v[162:163], v[168:169], v[136:137], v[162:163]
	v_pk_fma_f32 v[136:137], v[170:171], v[134:135], v[160:161]
	v_pk_fma_f32 v[174:175], v[166:167], v[134:135], v[174:175] neg_lo:[0,0,1] neg_hi:[0,0,1]
	s_nop 0
	v_cvt_pk_bf16_f32 v134, v174, v175
	v_cvt_pk_bf16_f32 v135, v172, v173
	v_cvt_pk_bf16_f32 v136, v136, v137
	v_cvt_pk_bf16_f32 v137, v162, v163

; __device__ __forceinline__ u32x4 pack8(const f32x4& a, const f32x4& b) { u32x4 w; w.x = cvt_pk_bf16(a[0], a[1]); w.y = cvt_pk_bf16(a[2], a[3]); w.z = cvt_pk_bf16(b[0], b[1]); w.w = cvt_pk_bf16(b[2], b[3]); return w; }
; __device__ __forceinline__ float hsum4(const f32x4& v) { return (v[0] + v[1]) + (v[2] + v[3]); }
; #define EPI_ROWS_END asm volatile("" ::: "memory"); }
;     __device__ __forceinline__ void operator()(const f32x4 (&acc)[2][2][4][2], const Unit& u, int wr, int wc, int fr, int fq) const {
;         EPI_LAUNDER const int cb = wc * 32 + 8 * fq; bf16_t* dst = (u.pn < 2 ? kn : vb) + (u.pn & 1) * 256;
;         f32x4 rnx = *(const f32x4*)(rskv + 4 * (size_t)(u.pm * BM + wr * 64 + fr));
;         EPI_ROWS_BEGIN
;             const float r = rsqrtf(hsum4(rnx) * (1.f / 128.f) + EPS);
;             { const int nx_ = ai * 4 + m + 1; if (nx_ < 8) rnx = *(const f32x4*)(rskv + 4 * (size_t)(u.pm * BM + (nx_ >> 2) * HALF + wr * 64 + (nx_ & 3) * 16 + fr)); }
; #pragma unroll
;             for (int bj = 0; bj < 2; ++bj) *(u32x4*)(dst + (size_t)row * 512 + bj * HALF + cb) = pack8(acc[ai][bj][m][0] * r, acc[ai][bj][m][1] * r);
;         EPI_ROWS_END
.LBB0_863:
	s_cmp_lt_i32 s72, 2
	s_mov_b32 s1, 0x10658100
	s_cselect_b32 s1, s1, 0x11758100
	s_add_u32 s1, s26, s1
	s_addc_u32 s7, s27, 0
	s_lshl_b32 s6, s72, 9
	s_and_b32 s6, s6, 0x200
	s_add_u32 s6, s1, s6
	s_addc_u32 s7, s7, 0
	s_lshl_b32 s1, s56, 8
	s_add_i32 s1, s1, s55
	v_mbcnt_lo_u32_b32 v137, -1, 0
	v_mbcnt_hi_u32_b32 v137, -1, v137
	s_brev_b32 s38, 60
	v_and_or_b32 v140, v137, 15, s1
	v_ashrrev_i32_e32 v141, 31, v140
	v_lshl_add_u64 v[138:139], v[140:141], 4, s[12:13]
	s_mov_b32 s98, m0
	s_mov_b32 m0, 0x20400
	s_nop 0
	global_load_lds_dword v[138:139], off offset:256
	global_load_lds_dword v[138:139], off offset:512
	global_load_lds_dword v[138:139], off offset:768
	global_load_lds_dword v[138:139], off offset:2048
	global_load_lds_dword v[138:139], off offset:2304
	global_load_lds_dword v[138:139], off offset:2560
	global_load_lds_dword v[138:139], off offset:2816
	s_mov_b32 m0, s98
	global_load_dwordx4 v[146:149], v[138:139], off
	v_or_b32_e32 v142, 16, v140
	v_ashrrev_i32_e32 v143, 31, v142
	v_ashrrev_i32_e32 v136, 1, v137
	v_and_b32_e32 v136, -8, v136
	v_add_u32_e32 v136, s58, v136
	v_ashrrev_i32_e32 v137, 31, v136
	v_lshl_add_u64 v[136:137], v[136:137], 1, s[6:7]
	s_mov_b32 s6, 0x358637bd
	v_lshlrev_b64 v[150:151], 10, v[140:141]
	v_lshl_add_u64 v[150:151], v[136:137], 0, v[150:151]
	v_mov_b32_e32 v236, v242
	s_waitcnt vmcnt(0)
	v_mov_b32_e32 v138, v147
	v_mov_b32_e32 v139, v148
	v_mov_b32_e32 v147, v149
	v_pk_add_f32 v[138:139], v[138:139], v[146:147]
	v_lshl_add_u64 v[146:147], v[142:143], 4, s[12:13]
	global_load_dwordx4 v[146:149], v[146:147], off
	s_waitcnt vmcnt(0)
	v_mov_b32_e32 v152, v147
	v_mov_b32_e32 v153, v148
	v_mov_b32_e32 v147, v149
	v_pk_add_f32 v[146:147], v[152:153], v[146:147]
	v_mov_b32_e32 v149, v138
	v_mov_b32_e32 v148, v146
	v_mov_b32_e32 v138, v147
	v_pk_add_f32 v[146:147], v[148:149], v[138:139]
	v_mov_b64_e32 v[138:139], s[6:7]
	v_pk_fma_f32 v[146:147], v[146:147], s[38:39], v[138:139] op_sel_hi:[1,0,0]
	s_nop 0
	v_mul_f32_e32 v141, 0x4b800000, v147
	v_cmp_gt_f32_e64 s[6:7], s31, v147
	v_cmp_gt_f32_e32 vcc, s31, v146
	s_nop 0
	v_cndmask_b32_e64 v141, v147, v141, s[6:7]
	v_rsq_f32_e32 v141, v141
	s_nop 0
	v_mul_f32_e32 v147, 0x45800000, v141
	v_cndmask_b32_e64 v148, v141, v147, s[6:7]
	v_pk_mul_f32 v[114:115], v[114:115], v[148:149] op_sel_hi:[1,0]
	v_pk_mul_f32 v[116:117], v[116:117], v[148:149] op_sel_hi:[1,0]
	v_cvt_pk_bf16_f32 v114, v114, v115
	v_pk_mul_f32 v[120:121], v[120:121], v[148:149] op_sel_hi:[1,0]
	v_cvt_pk_bf16_f32 v115, v116, v117
	v_pk_mul_f32 v[118:119], v[118:119], v[148:149] op_sel_hi:[1,0]
	s_nop 0
	v_cvt_pk_bf16_f32 v116, v118, v119
	v_cvt_pk_bf16_f32 v117, v120, v121
	global_store_dwordx4 v[150:151], v[114:117], off
	v_pk_mul_f32 v[118:119], v[128:129], v[148:149] op_sel_hi:[1,0]
	v_pk_mul_f32 v[120:121], v[126:127], v[148:149] op_sel_hi:[1,0]
	v_pk_mul_f32 v[114:115], v[122:123], v[148:149] op_sel_hi:[1,0]
	v_pk_mul_f32 v[116:117], v[124:125], v[148:149] op_sel_hi:[1,0]
	v_cvt_pk_bf16_f32 v114, v114, v115
	v_lshlrev_b64 v[122:123], 10, v[142:143]
	v_cvt_pk_bf16_f32 v115, v116, v117
	v_cvt_pk_bf16_f32 v116, v120, v121
	v_cvt_pk_bf16_f32 v117, v118, v119
	global_store_dwordx4 v[150:151], v[114:117], off offset:256
	v_lshl_add_u64 v[122:123], v[136:137], 0, v[122:123]
	s_nop 0
	v_mul_f32_e32 v114, 0x4b800000, v146
	v_cndmask_b32_e32 v114, v146, v114, vcc
	v_rsq_f32_e32 v114, v114
	s_nop 0
	v_mul_f32_e32 v115, 0x45800000, v114
	v_cndmask_b32_e32 v120, v114, v115, vcc
	v_or_b32_e32 v114, 32, v140
	v_ashrrev_i32_e32 v115, 31, v114
	v_lshl_add_u64 v[116:117], v[114:115], 4, s[12:13]
	global_load_dwordx4 v[116:119], v[116:117], off
	v_pk_mul_f32 v[98:99], v[98:99], v[120:121] op_sel_hi:[1,0]
	v_pk_mul_f32 v[100:101], v[100:101], v[120:121] op_sel_hi:[1,0]
	v_cvt_pk_bf16_f32 v98, v98, v99
	v_pk_mul_f32 v[104:105], v[104:105], v[120:121] op_sel_hi:[1,0]
	v_cvt_pk_bf16_f32 v99, v100, v101
	v_pk_mul_f32 v[102:103], v[102:103], v[120:121] op_sel_hi:[1,0]
	s_nop 0
	v_cvt_pk_bf16_f32 v100, v102, v103
	v_cvt_pk_bf16_f32 v101, v104, v105
	global_store_dwordx4 v[122:123], v[98:101], off
	v_pk_mul_f32 v[102:103], v[112:113], v[120:121] op_sel_hi:[1,0]
	v_pk_mul_f32 v[104:105], v[110:111], v[120:121] op_sel_hi:[1,0]
	v_pk_mul_f32 v[98:99], v[106:107], v[120:121] op_sel_hi:[1,0]
	v_pk_mul_f32 v[100:101], v[108:109], v[120:121] op_sel_hi:[1,0]
	v_cvt_pk_bf16_f32 v98, v98, v99
	v_lshlrev_b64 v[106:107], 10, v[114:115]
	v_cvt_pk_bf16_f32 v99, v100, v101
	v_cvt_pk_bf16_f32 v100, v104, v105
	v_cvt_pk_bf16_f32 v101, v102, v103
	global_store_dwordx4 v[122:123], v[98:101], off offset:256
	v_lshl_add_u64 v[106:107], v[136:137], 0, v[106:107]
	s_waitcnt vmcnt(2)
	v_mov_b32_e32 v98, v117
	v_mov_b32_e32 v99, v118
	v_mov_b32_e32 v117, v119
	v_pk_add_f32 v[100:101], v[98:99], v[116:117]
	v_or_b32_e32 v98, 48, v140
	v_ashrrev_i32_e32 v99, 31, v98
	v_lshl_add_u64 v[102:103], v[98:99], 4, s[12:13]
	global_load_dwordx4 v[102:105], v[102:103], off
	s_waitcnt vmcnt(0)
; __device__ __forceinline__ u32x4 pack8(const f32x4& a, const f32x4& b) { u32x4 w; w.x = cvt_pk_bf16(a[0], a[1]); w.y = cvt_pk_bf16(a[2], a[3]); w.z = cvt_pk_bf16(b[0], b[1]); w.w = cvt_pk_bf16(b[2], b[3]); return w; }
; __device__ __forceinline__ float hsum4(const f32x4& v) { return (v[0] + v[1]) + (v[2] + v[3]); }
; #define EPI_ROWS_END asm volatile("" ::: "memory"); }
;     __device__ __forceinline__ void operator()(const f32x4 (&acc)[2][2][4][2], const Unit& u, int wr, int wc, int fr, int fq) const {
;     ...
;         f32x4 rnx = *(const f32x4*)(rskv + 4 * (size_t)(u.pm * BM + wr * 64 + fr));
;         EPI_ROWS_BEGIN
;             const float r = rsqrtf(hsum4(rnx) * (1.f / 128.f) + EPS);
;             { const int nx_ = ai * 4 + m + 1; if (nx_ < 8) rnx = *(const f32x4*)(rskv + 4 * (size_t)(u.pm * BM + (nx_ >> 2) * HALF + wr * 64 + (nx_ & 3) * 16 + fr)); }
; #pragma unroll
;             for (int bj = 0; bj < 2; ++bj) *(u32x4*)(dst + (size_t)row * 512 + bj * HALF + cb) = pack8(acc[ai][bj][m][0] * r, acc[ai][bj][m][1] * r);
;         EPI_ROWS_END
	v_mov_b32_e32 v108, v103
	v_mov_b32_e32 v109, v104
	v_mov_b32_e32 v103, v105
	v_pk_add_f32 v[102:103], v[108:109], v[102:103]
	v_mov_b32_e32 v105, v100
	v_mov_b32_e32 v104, v102
	v_mov_b32_e32 v100, v103
	v_pk_add_f32 v[100:101], v[104:105], v[100:101]
	s_nop 0
	v_pk_fma_f32 v[100:101], v[100:101], s[38:39], v[138:139] op_sel_hi:[1,0,0]
	s_nop 0
	v_mul_f32_e32 v102, 0x4b800000, v101
	v_cmp_gt_f32_e64 s[6:7], s31, v101
	v_cmp_gt_f32_e32 vcc, s31, v100
	s_nop 0
	v_cndmask_b32_e64 v101, v101, v102, s[6:7]
	v_rsq_f32_e32 v101, v101
	s_nop 0
	v_mul_f32_e32 v102, 0x45800000, v101
	v_cndmask_b32_e64 v102, v101, v102, s[6:7]
	v_pk_mul_f32 v[82:83], v[82:83], v[102:103] op_sel_hi:[1,0]
	v_pk_mul_f32 v[84:85], v[84:85], v[102:103] op_sel_hi:[1,0]
	v_cvt_pk_bf16_f32 v82, v82, v83
	v_pk_mul_f32 v[88:89], v[88:89], v[102:103] op_sel_hi:[1,0]
	v_cvt_pk_bf16_f32 v83, v84, v85
	v_pk_mul_f32 v[86:87], v[86:87], v[102:103] op_sel_hi:[1,0]
	s_nop 0
	v_cvt_pk_bf16_f32 v84, v86, v87
	v_cvt_pk_bf16_f32 v85, v88, v89
	global_store_dwordx4 v[106:107], v[82:85], off
	v_pk_mul_f32 v[86:87], v[96:97], v[102:103] op_sel_hi:[1,0]
	v_pk_mul_f32 v[88:89], v[94:95], v[102:103] op_sel_hi:[1,0]
	v_pk_mul_f32 v[82:83], v[90:91], v[102:103] op_sel_hi:[1,0]
	v_pk_mul_f32 v[84:85], v[92:93], v[102:103] op_sel_hi:[1,0]
	v_cvt_pk_bf16_f32 v82, v82, v83
	v_lshlrev_b64 v[90:91], 10, v[98:99]
	v_cvt_pk_bf16_f32 v83, v84, v85
	v_cvt_pk_bf16_f32 v84, v88, v89
	v_cvt_pk_bf16_f32 v85, v86, v87
	global_store_dwordx4 v[106:107], v[82:85], off offset:256
	v_lshl_add_u64 v[90:91], v[136:137], 0, v[90:91]
	s_nop 0
	v_mul_f32_e32 v82, 0x4b800000, v100
	v_cndmask_b32_e32 v82, v100, v82, vcc
	v_rsq_f32_e32 v82, v82
	s_nop 0
	v_mul_f32_e32 v83, 0x45800000, v82
	v_cndmask_b32_e32 v88, v82, v83, vcc
	v_add_u32_e32 v82, 0x80, v140
	v_ashrrev_i32_e32 v83, 31, v82
	v_lshl_add_u64 v[84:85], v[82:83], 4, s[12:13]
	global_load_dwordx4 v[84:87], v[84:85], off
	v_pk_mul_f32 v[66:67], v[66:67], v[88:89] op_sel_hi:[1,0]
	v_pk_mul_f32 v[68:69], v[68:69], v[88:89] op_sel_hi:[1,0]
	v_cvt_pk_bf16_f32 v66, v66, v67
	v_pk_mul_f32 v[72:73], v[72:73], v[88:89] op_sel_hi:[1,0]
	v_cvt_pk_bf16_f32 v67, v68, v69
	v_pk_mul_f32 v[70:71], v[70:71], v[88:89] op_sel_hi:[1,0]
	s_nop 0
	v_cvt_pk_bf16_f32 v68, v70, v71
	v_cvt_pk_bf16_f32 v69, v72, v73
	global_store_dwordx4 v[90:91], v[66:69], off
	v_pk_mul_f32 v[70:71], v[80:81], v[88:89] op_sel_hi:[1,0]
	v_pk_mul_f32 v[72:73], v[78:79], v[88:89] op_sel_hi:[1,0]
	v_pk_mul_f32 v[66:67], v[74:75], v[88:89] op_sel_hi:[1,0]
	v_pk_mul_f32 v[68:69], v[76:77], v[88:89] op_sel_hi:[1,0]
	v_cvt_pk_bf16_f32 v66, v66, v67
	v_lshlrev_b64 v[74:75], 10, v[82:83]
	v_cvt_pk_bf16_f32 v67, v68, v69
	v_cvt_pk_bf16_f32 v68, v72, v73
	v_cvt_pk_bf16_f32 v69, v70, v71
	global_store_dwordx4 v[90:91], v[66:69], off offset:256
	v_lshl_add_u64 v[74:75], v[136:137], 0, v[74:75]
	s_waitcnt vmcnt(2)
	v_mov_b32_e32 v66, v85
	v_mov_b32_e32 v67, v86
	v_mov_b32_e32 v85, v87
	v_pk_add_f32 v[68:69], v[66:67], v[84:85]
	v_add_u32_e32 v66, 0x90, v140
	v_ashrrev_i32_e32 v67, 31, v66
	v_lshl_add_u64 v[70:71], v[66:67], 4, s[12:13]
	global_load_dwordx4 v[70:73], v[70:71], off
	s_waitcnt vmcnt(0)
; __device__ __forceinline__ u32x4 pack8(const f32x4& a, const f32x4& b) { u32x4 w; w.x = cvt_pk_bf16(a[0], a[1]); w.y = cvt_pk_bf16(a[2], a[3]); w.z = cvt_pk_bf16(b[0], b[1]); w.w = cvt_pk_bf16(b[2], b[3]); return w; }
; __device__ __forceinline__ float hsum4(const f32x4& v) { return (v[0] + v[1]) + (v[2] + v[3]); }
; #define EPI_ROWS_END asm volatile("" ::: "memory"); }
;     __device__ __forceinline__ void operator()(const f32x4 (&acc)[2][2][4][2], const Unit& u, int wr, int wc, int fr, int fq) const {
;     ...
;         f32x4 rnx = *(const f32x4*)(rskv + 4 * (size_t)(u.pm * BM + wr * 64 + fr));
;         EPI_ROWS_BEGIN
;             const float r = rsqrtf(hsum4(rnx) * (1.f / 128.f) + EPS);
;             { const int nx_ = ai * 4 + m + 1; if (nx_ < 8) rnx = *(const f32x4*)(rskv + 4 * (size_t)(u.pm * BM + (nx_ >> 2) * HALF + wr * 64 + (nx_ & 3) * 16 + fr)); }
; #pragma unroll
;             for (int bj = 0; bj < 2; ++bj) *(u32x4*)(dst + (size_t)row * 512 + bj * HALF + cb) = pack8(acc[ai][bj][m][0] * r, acc[ai][bj][m][1] * r);
;         EPI_ROWS_END
	v_mov_b32_e32 v76, v71
	v_mov_b32_e32 v77, v72
	v_mov_b32_e32 v71, v73
	v_pk_add_f32 v[70:71], v[76:77], v[70:71]
	v_mov_b32_e32 v73, v68
	v_mov_b32_e32 v72, v70
	v_mov_b32_e32 v68, v71
	v_pk_add_f32 v[68:69], v[72:73], v[68:69]
	s_nop 0
	v_pk_fma_f32 v[68:69], v[68:69], s[38:39], v[138:139] op_sel_hi:[1,0,0]
	s_nop 0
	v_mul_f32_e32 v70, 0x4b800000, v69
	v_cmp_gt_f32_e64 s[6:7], s31, v69
	v_cmp_gt_f32_e32 vcc, s31, v68
	s_nop 0
	v_cndmask_b32_e64 v69, v69, v70, s[6:7]
	v_rsq_f32_e32 v69, v69
	s_nop 0
	v_mul_f32_e32 v70, 0x45800000, v69
	v_cndmask_b32_e64 v70, v69, v70, s[6:7]
	v_pk_mul_f32 v[50:51], v[50:51], v[70:71] op_sel_hi:[1,0]
	v_pk_mul_f32 v[52:53], v[52:53], v[70:71] op_sel_hi:[1,0]
	v_cvt_pk_bf16_f32 v50, v50, v51
	v_pk_mul_f32 v[56:57], v[56:57], v[70:71] op_sel_hi:[1,0]
	v_cvt_pk_bf16_f32 v51, v52, v53
	v_pk_mul_f32 v[54:55], v[54:55], v[70:71] op_sel_hi:[1,0]
	s_nop 0
	v_cvt_pk_bf16_f32 v52, v54, v55
	v_cvt_pk_bf16_f32 v53, v56, v57
	global_store_dwordx4 v[74:75], v[50:53], off
	v_pk_mul_f32 v[54:55], v[64:65], v[70:71] op_sel_hi:[1,0]
	v_pk_mul_f32 v[56:57], v[62:63], v[70:71] op_sel_hi:[1,0]
	v_pk_mul_f32 v[50:51], v[58:59], v[70:71] op_sel_hi:[1,0]
	v_pk_mul_f32 v[52:53], v[60:61], v[70:71] op_sel_hi:[1,0]
	v_cvt_pk_bf16_f32 v50, v50, v51
	v_lshlrev_b64 v[58:59], 10, v[66:67]
	v_cvt_pk_bf16_f32 v51, v52, v53
	v_cvt_pk_bf16_f32 v52, v56, v57
	v_cvt_pk_bf16_f32 v53, v54, v55
	global_store_dwordx4 v[74:75], v[50:53], off offset:256
	v_lshl_add_u64 v[58:59], v[136:137], 0, v[58:59]
	s_nop 0
	v_mul_f32_e32 v50, 0x4b800000, v68
	v_cndmask_b32_e32 v50, v68, v50, vcc
	v_rsq_f32_e32 v50, v50
	s_nop 0
	v_mul_f32_e32 v51, 0x45800000, v50
	v_cndmask_b32_e32 v56, v50, v51, vcc
	v_add_u32_e32 v50, 0xa0, v140
	v_ashrrev_i32_e32 v51, 31, v50
	v_lshl_add_u64 v[52:53], v[50:51], 4, s[12:13]
	global_load_dwordx4 v[52:55], v[52:53], off
	v_pk_mul_f32 v[34:35], v[34:35], v[56:57] op_sel_hi:[1,0]
	v_pk_mul_f32 v[36:37], v[36:37], v[56:57] op_sel_hi:[1,0]
	v_cvt_pk_bf16_f32 v34, v34, v35
	v_pk_mul_f32 v[40:41], v[40:41], v[56:57] op_sel_hi:[1,0]
	v_cvt_pk_bf16_f32 v35, v36, v37
	v_pk_mul_f32 v[38:39], v[38:39], v[56:57] op_sel_hi:[1,0]
	s_nop 0
	v_cvt_pk_bf16_f32 v36, v38, v39
	v_cvt_pk_bf16_f32 v37, v40, v41
	global_store_dwordx4 v[58:59], v[34:37], off
	v_pk_mul_f32 v[38:39], v[48:49], v[56:57] op_sel_hi:[1,0]
	v_pk_mul_f32 v[40:41], v[46:47], v[56:57] op_sel_hi:[1,0]
	v_pk_mul_f32 v[34:35], v[42:43], v[56:57] op_sel_hi:[1,0]
	v_pk_mul_f32 v[36:37], v[44:45], v[56:57] op_sel_hi:[1,0]
	v_cvt_pk_bf16_f32 v34, v34, v35
	v_lshlrev_b64 v[42:43], 10, v[50:51]
	v_cvt_pk_bf16_f32 v35, v36, v37
	v_cvt_pk_bf16_f32 v36, v40, v41
	v_cvt_pk_bf16_f32 v37, v38, v39
	global_store_dwordx4 v[58:59], v[34:37], off offset:256
	v_lshl_add_u64 v[42:43], v[136:137], 0, v[42:43]
	s_waitcnt vmcnt(2)
	v_mov_b32_e32 v34, v53
	v_mov_b32_e32 v35, v54
	v_mov_b32_e32 v53, v55
	v_pk_add_f32 v[36:37], v[34:35], v[52:53]
	v_add_u32_e32 v34, 0xb0, v140
	v_ashrrev_i32_e32 v35, 31, v34
	v_lshl_add_u64 v[38:39], v[34:35], 4, s[12:13]
	global_load_dwordx4 v[38:41], v[38:39], off
	s_waitcnt vmcnt(0)
	v_mov_b32_e32 v44, v39
	v_mov_b32_e32 v45, v40
	v_mov_b32_e32 v39, v41
	v_pk_add_f32 v[38:39], v[44:45], v[38:39]
	v_mov_b32_e32 v41, v36
	v_mov_b32_e32 v40, v38
	v_mov_b32_e32 v36, v39
	v_pk_add_f32 v[36:37], v[40:41], v[36:37]
	s_nop 0
	v_pk_fma_f32 v[36:37], v[36:37], s[38:39], v[138:139] op_sel_hi:[1,0,0]
	s_nop 0
	v_mul_f32_e32 v38, 0x4b800000, v37
	v_cmp_gt_f32_e64 s[6:7], s31, v37
	v_cmp_gt_f32_e32 vcc, s31, v36
	s_nop 0
	v_cndmask_b32_e64 v37, v37, v38, s[6:7]
	v_rsq_f32_e32 v37, v37
	s_nop 0
	v_mul_f32_e32 v38, 0x45800000, v37
	v_cndmask_b32_e64 v38, v37, v38, s[6:7]
	v_pk_mul_f32 v[18:19], v[18:19], v[38:39] op_sel_hi:[1,0]
	v_pk_mul_f32 v[20:21], v[20:21], v[38:39] op_sel_hi:[1,0]
	v_cvt_pk_bf16_f32 v18, v18, v19
	v_pk_mul_f32 v[24:25], v[24:25], v[38:39] op_sel_hi:[1,0]
	v_cvt_pk_bf16_f32 v19, v20, v21
	v_pk_mul_f32 v[22:23], v[22:23], v[38:39] op_sel_hi:[1,0]
	s_mov_b64 s[6:7], -1
	v_cvt_pk_bf16_f32 v20, v22, v23
	v_cvt_pk_bf16_f32 v21, v24, v25
	global_store_dwordx4 v[42:43], v[18:21], off
	v_pk_mul_f32 v[22:23], v[32:33], v[38:39] op_sel_hi:[1,0]
	v_pk_mul_f32 v[24:25], v[30:31], v[38:39] op_sel_hi:[1,0]
	v_pk_mul_f32 v[18:19], v[26:27], v[38:39] op_sel_hi:[1,0]
	v_pk_mul_f32 v[20:21], v[28:29], v[38:39] op_sel_hi:[1,0]
	v_cvt_pk_bf16_f32 v18, v18, v19
	s_nop 0
	v_cvt_pk_bf16_f32 v19, v20, v21
	v_cvt_pk_bf16_f32 v20, v24, v25
	v_cvt_pk_bf16_f32 v21, v22, v23
	global_store_dwordx4 v[42:43], v[18:21], off offset:256
	s_nop 1
	v_mul_f32_e32 v18, 0x4b800000, v36
	v_cndmask_b32_e32 v18, v36, v18, vcc
	v_rsq_f32_e32 v18, v18
	v_lshlrev_b64 v[20:21], 10, v[34:35]
	v_lshl_add_u64 v[20:21], v[136:137], 0, v[20:21]
	v_mul_f32_e32 v19, 0x45800000, v18
	v_cndmask_b32_e32 v18, v18, v19, vcc
	v_pk_mul_f32 v[16:17], v[16:17], v[18:19] op_sel_hi:[1,0]
	v_pk_mul_f32 v[14:15], v[14:15], v[18:19] op_sel_hi:[1,0]
	v_pk_mul_f32 v[22:23], v[12:13], v[18:19] op_sel_hi:[1,0]
	v_pk_mul_f32 v[12:13], v[10:11], v[18:19] op_sel_hi:[1,0]
	v_cvt_pk_bf16_f32 v10, v14, v15
	v_cvt_pk_bf16_f32 v11, v16, v17
	v_pk_mul_f32 v[8:9], v[8:9], v[18:19] op_sel_hi:[1,0]
	v_cvt_pk_bf16_f32 v12, v12, v13
	v_cvt_pk_bf16_f32 v13, v22, v23
	global_store_dwordx4 v[20:21], v[10:13], off
	v_pk_mul_f32 v[6:7], v[6:7], v[18:19] op_sel_hi:[1,0]
	s_andn2_b64 vcc, exec, s[4:5]
	v_pk_mul_f32 v[10:11], v[4:5], v[18:19] op_sel_hi:[1,0]
	v_pk_mul_f32 v[4:5], v[2:3], v[18:19] op_sel_hi:[1,0]
	v_cvt_pk_bf16_f32 v2, v6, v7
	v_cvt_pk_bf16_f32 v3, v8, v9
	s_nop 0
	v_cvt_pk_bf16_f32 v4, v4, v5
	v_cvt_pk_bf16_f32 v5, v10, v11
	global_store_dwordx4 v[20:21], v[2:5], off offset:256
	s_cbranch_vccnz .LBB0_854
	s_andn2_b64 vcc, exec, s[10:11]
	s_cbranch_vccnz .LBB0_853
	s_barrier
	s_branch .LBB0_853
